# v7 + P3 row wave-sums via DPP/readlane instead of 6 ds_bpermute round trips + P6 FFN-down epilogue with all 16 residual tile loads issued up front (counted vmcnt)
# speedup vs baseline: 1.0092x; 1.0060x over previous
.LBB0_574:
	v_lshl_add_u64 v[16:17], s[64:65], 0, v[52:53]
	v_add_co_u32_e32 v18, vcc, 0x19bc5000, v16
	v_lshl_add_u64 v[20:21], s[18:19], 0, v[52:53]
	s_nop 0
	v_addc_co_u32_e32 v19, vcc, 0, v17, vcc
	v_add_co_u32_e32 v16, vcc, 0x1bcc5000, v16
	global_load_dwordx4 v[40:43], v[18:19], off
	s_nop 0
	v_addc_co_u32_e32 v17, vcc, 0, v17, vcc
	global_load_dwordx4 v[54:57], v[16:17], off
	v_lshl_add_u64 v[16:17], s[42:43], 0, v[52:53]
	v_add_co_u32_e32 v18, vcc, s45, v16
	s_add_i32 s7, s7, 32
	s_nop 0
	v_addc_co_u32_e32 v19, vcc, 0, v17, vcc
	v_add_co_u32_e32 v16, vcc, s46, v16
	global_load_dwordx4 v[32:35], v[18:19], off
	s_nop 0
	v_addc_co_u32_e32 v17, vcc, 0, v17, vcc
	global_load_dwordx4 v[36:39], v[16:17], off
	v_lshl_add_u64 v[16:17], s[38:39], 0, v[52:53]
	v_add_co_u32_e32 v18, vcc, s45, v16
	s_waitcnt vmcnt(3)
	v_lshlrev_b32_e32 v58, 16, v43
	v_and_b32_e32 v59, 0xffff0000, v43
	v_lshlrev_b32_e32 v62, 16, v42
	v_and_b32_e32 v63, 0xffff0000, v42
	s_waitcnt vmcnt(2)
	v_lshlrev_b32_e32 v42, 16, v56
	v_and_b32_e32 v43, 0xffff0000, v56
	s_waitcnt lgkmcnt(0)
	v_pk_fma_f32 v[42:43], v[12:13], v[42:43], v[62:63]
	v_lshlrev_b32_e32 v62, 16, v41
	v_and_b32_e32 v63, 0xffff0000, v41
	v_lshlrev_b32_e32 v66, 16, v40
	v_and_b32_e32 v67, 0xffff0000, v40
	v_lshlrev_b32_e32 v40, 16, v54
	v_and_b32_e32 v41, 0xffff0000, v54
	v_lshlrev_b32_e32 v64, 16, v55
	v_and_b32_e32 v65, 0xffff0000, v55
	v_pk_fma_f32 v[40:41], v[8:9], v[40:41], v[66:67]
	v_pk_fma_f32 v[62:63], v[10:11], v[64:65], v[62:63]
	v_pk_mul_f32 v[54:55], v[40:41], v[40:41]
	v_pk_mul_f32 v[64:65], v[62:63], v[62:63]
	v_add_f32_e32 v54, v54, v55
	v_add_f32_e32 v54, v64, v54
	v_lshlrev_b32_e32 v60, 16, v57
	v_and_b32_e32 v61, 0xffff0000, v57
	v_pk_mul_f32 v[56:57], v[42:43], v[42:43]
	v_add_f32_e32 v54, v65, v54
	v_pk_fma_f32 v[58:59], v[14:15], v[60:61], v[58:59]
	v_add_f32_e32 v54, v56, v54
	v_pk_mul_f32 v[60:61], v[58:59], v[58:59]
	v_add_f32_e32 v54, v57, v54
	v_add_f32_e32 v54, v60, v54
	v_add_f32_e32 v54, v61, v54
	v_addc_co_u32_e32 v19, vcc, 0, v17, vcc
	v_add_co_u32_e32 v16, vcc, s46, v16
	s_waitcnt lgkmcnt(0)
	v_addc_co_u32_e32 v17, vcc, 0, v17, vcc
	global_load_dwordx4 v[24:27], v[18:19], off
	global_load_dwordx4 v[28:31], v[16:17], off
	s_waitcnt lgkmcnt(0)
	v_add_co_u32_e32 v16, vcc, s45, v20
	s_waitcnt lgkmcnt(0)
	v_addc_co_u32_e32 v17, vcc, 0, v21, vcc
	v_add_co_u32_e32 v20, vcc, s46, v20
	s_waitcnt lgkmcnt(0)
	v_addc_co_u32_e32 v21, vcc, 0, v21, vcc
	global_load_dwordx4 v[16:19], v[16:17], off
	s_waitcnt lgkmcnt(0)
	global_load_dwordx4 v[20:23], v[20:21], off
	s_waitcnt lgkmcnt(0)
	s_nop 1
	v_add_f32_dpp v54, v54, v54 quad_perm:[1,0,3,2] row_mask:0xf bank_mask:0xf
	s_nop 1
	v_add_f32_dpp v54, v54, v54 quad_perm:[2,3,0,1] row_mask:0xf bank_mask:0xf
	s_nop 1
	v_add_f32_dpp v54, v54, v54 row_half_mirror row_mask:0xf bank_mask:0xf
	s_nop 1
	v_add_f32_dpp v54, v54, v54 row_mirror row_mask:0xf bank_mask:0xf
	s_nop 1
	v_readlane_b32 s98, v54, 0
	v_readlane_b32 s99, v54, 16
	v_readlane_b32 s100, v54, 32
	v_readlane_b32 s101, v54, 48
	s_nop 1
	v_mov_b32_e32 v54, s98
	v_add_f32_e32 v54, s99, v54
	v_add_f32_e32 v54, s100, v54
	v_add_f32_e32 v54, s101, v54
	v_fmamk_f32 v54, v54, 0x3b000000, v77
	v_rsq_f32_e32 v54, v54
	s_nop 0
	v_pk_mul_f32 v[40:41], v[40:41], v[54:55] op_sel_hi:[1,0]
	v_pk_mul_f32 v[56:57], v[62:63], v[54:55] op_sel_hi:[1,0]
	v_pk_mul_f32 v[42:43], v[42:43], v[54:55] op_sel_hi:[1,0]
	v_pk_mul_f32 v[54:55], v[58:59], v[54:55] op_sel_hi:[1,0]
	v_pk_mul_f32 v[40:41], v[0:1], v[40:41]
	v_pk_mul_f32 v[56:57], v[2:3], v[56:57]
	v_pk_mul_f32 v[42:43], v[4:5], v[42:43]
	v_pk_mul_f32 v[54:55], v[6:7], v[54:55]
	v_cvt_pk_bf16_f32 v40, v40, v41
	v_cvt_pk_bf16_f32 v41, v56, v57
	v_cvt_pk_bf16_f32 v42, v42, v43
	v_cvt_pk_bf16_f32 v43, v54, v55
	v_lshl_add_u64 v[54:55], s[60:61], 0, v[52:53]
	global_store_dwordx4 v[54:55], v[40:43], off
	s_waitcnt vmcnt(6)
	v_lshlrev_b32_e32 v54, 16, v34
	v_and_b32_e32 v55, 0xffff0000, v34
	v_lshlrev_b32_e32 v40, 16, v35
	v_and_b32_e32 v41, 0xffff0000, v35
	s_waitcnt vmcnt(5)
	v_lshlrev_b32_e32 v34, 16, v38
	v_and_b32_e32 v35, 0xffff0000, v38
	v_pk_fma_f32 v[34:35], v[12:13], v[34:35], v[54:55]
	v_lshlrev_b32_e32 v54, 16, v33
	v_and_b32_e32 v55, 0xffff0000, v33
	v_lshlrev_b32_e32 v58, 16, v32
	v_and_b32_e32 v59, 0xffff0000, v32
	v_lshlrev_b32_e32 v32, 16, v36
	v_and_b32_e32 v33, 0xffff0000, v36
	v_lshlrev_b32_e32 v56, 16, v37
	v_and_b32_e32 v57, 0xffff0000, v37
	v_pk_fma_f32 v[32:33], v[8:9], v[32:33], v[58:59]
	v_pk_fma_f32 v[54:55], v[10:11], v[56:57], v[54:55]
	v_pk_mul_f32 v[36:37], v[32:33], v[32:33]
	v_pk_mul_f32 v[56:57], v[54:55], v[54:55]
	v_add_f32_e32 v36, v36, v37
	v_add_f32_e32 v36, v56, v36
	v_lshlrev_b32_e32 v42, 16, v39
	v_and_b32_e32 v43, 0xffff0000, v39
	v_pk_mul_f32 v[38:39], v[34:35], v[34:35]
	v_add_f32_e32 v36, v57, v36
	v_pk_fma_f32 v[40:41], v[14:15], v[42:43], v[40:41]
	v_add_f32_e32 v36, v38, v36
	v_pk_mul_f32 v[42:43], v[40:41], v[40:41]
	v_add_f32_e32 v36, v39, v36
	v_add_f32_e32 v36, v42, v36
	v_add_f32_e32 v36, v43, v36
	s_waitcnt lgkmcnt(0)
	s_waitcnt lgkmcnt(0)
	s_waitcnt lgkmcnt(0)
	s_waitcnt lgkmcnt(0)
	s_waitcnt lgkmcnt(0)
	s_waitcnt lgkmcnt(0)
	s_nop 1
	v_add_f32_dpp v36, v36, v36 quad_perm:[1,0,3,2] row_mask:0xf bank_mask:0xf
	s_nop 1
	v_add_f32_dpp v36, v36, v36 quad_perm:[2,3,0,1] row_mask:0xf bank_mask:0xf
	s_nop 1
	v_add_f32_dpp v36, v36, v36 row_half_mirror row_mask:0xf bank_mask:0xf
	s_nop 1
	v_add_f32_dpp v36, v36, v36 row_mirror row_mask:0xf bank_mask:0xf
	s_nop 1
	v_readlane_b32 s98, v36, 0
	v_readlane_b32 s99, v36, 16
	v_readlane_b32 s100, v36, 32
	v_readlane_b32 s101, v36, 48
	s_nop 1
	v_mov_b32_e32 v36, s98
	v_add_f32_e32 v36, s99, v36
	v_add_f32_e32 v36, s100, v36
	v_add_f32_e32 v36, s101, v36
	v_fmamk_f32 v36, v36, 0x3b000000, v77
	v_rsq_f32_e32 v36, v36
	s_nop 0
	v_pk_mul_f32 v[32:33], v[32:33], v[36:37] op_sel_hi:[1,0]
	v_pk_mul_f32 v[38:39], v[54:55], v[36:37] op_sel_hi:[1,0]
	v_pk_mul_f32 v[34:35], v[34:35], v[36:37] op_sel_hi:[1,0]
	v_pk_mul_f32 v[36:37], v[40:41], v[36:37] op_sel_hi:[1,0]
	v_pk_mul_f32 v[32:33], v[0:1], v[32:33]
	v_pk_mul_f32 v[38:39], v[2:3], v[38:39]
	v_pk_mul_f32 v[34:35], v[4:5], v[34:35]
	v_pk_mul_f32 v[36:37], v[6:7], v[36:37]
	v_cvt_pk_bf16_f32 v32, v32, v33
	v_cvt_pk_bf16_f32 v33, v38, v39
	v_cvt_pk_bf16_f32 v34, v34, v35
	v_cvt_pk_bf16_f32 v35, v36, v37
	v_lshl_add_u64 v[36:37], s[40:41], 0, v[52:53]
	global_store_dwordx4 v[36:37], v[32:35], off
	s_waitcnt vmcnt(5)
	v_lshlrev_b32_e32 v36, 16, v26
	v_and_b32_e32 v37, 0xffff0000, v26
	v_lshlrev_b32_e32 v32, 16, v27
	v_and_b32_e32 v33, 0xffff0000, v27
	s_waitcnt vmcnt(4)
	v_lshlrev_b32_e32 v26, 16, v30
	v_and_b32_e32 v27, 0xffff0000, v30
	v_pk_fma_f32 v[26:27], v[12:13], v[26:27], v[36:37]
	v_lshlrev_b32_e32 v36, 16, v25
	v_and_b32_e32 v37, 0xffff0000, v25
	v_lshlrev_b32_e32 v40, 16, v24
	v_and_b32_e32 v41, 0xffff0000, v24
	v_lshlrev_b32_e32 v24, 16, v28
	v_and_b32_e32 v25, 0xffff0000, v28
	v_lshlrev_b32_e32 v38, 16, v29
	v_and_b32_e32 v39, 0xffff0000, v29
	v_pk_fma_f32 v[24:25], v[8:9], v[24:25], v[40:41]
	v_pk_fma_f32 v[36:37], v[10:11], v[38:39], v[36:37]
	v_pk_mul_f32 v[28:29], v[24:25], v[24:25]
	v_pk_mul_f32 v[38:39], v[36:37], v[36:37]
	v_add_f32_e32 v28, v28, v29
	v_add_f32_e32 v28, v38, v28
	v_lshlrev_b32_e32 v34, 16, v31
	v_and_b32_e32 v35, 0xffff0000, v31
	v_pk_mul_f32 v[30:31], v[26:27], v[26:27]
	v_add_f32_e32 v28, v39, v28
	v_pk_fma_f32 v[32:33], v[14:15], v[34:35], v[32:33]
	v_add_f32_e32 v28, v30, v28
	v_pk_mul_f32 v[34:35], v[32:33], v[32:33]
	v_add_f32_e32 v28, v31, v28
	v_add_f32_e32 v28, v34, v28
	v_add_f32_e32 v28, v35, v28
	s_waitcnt lgkmcnt(0)
	s_waitcnt lgkmcnt(0)
	s_waitcnt lgkmcnt(0)
	s_waitcnt lgkmcnt(0)
	s_waitcnt lgkmcnt(0)
	s_waitcnt lgkmcnt(0)
	s_nop 1
	v_add_f32_dpp v28, v28, v28 quad_perm:[1,0,3,2] row_mask:0xf bank_mask:0xf
	s_nop 1
	v_add_f32_dpp v28, v28, v28 quad_perm:[2,3,0,1] row_mask:0xf bank_mask:0xf
	s_nop 1
	v_add_f32_dpp v28, v28, v28 row_half_mirror row_mask:0xf bank_mask:0xf
	s_nop 1
	v_add_f32_dpp v28, v28, v28 row_mirror row_mask:0xf bank_mask:0xf
	s_nop 1
	v_readlane_b32 s98, v28, 0
	v_readlane_b32 s99, v28, 16
	v_readlane_b32 s100, v28, 32
	v_readlane_b32 s101, v28, 48
	s_nop 1
	v_mov_b32_e32 v28, s98
	v_add_f32_e32 v28, s99, v28
	v_add_f32_e32 v28, s100, v28
	v_add_f32_e32 v28, s101, v28
	v_fmamk_f32 v28, v28, 0x3b000000, v77
	v_rsq_f32_e32 v28, v28
	s_nop 0
	v_pk_mul_f32 v[24:25], v[24:25], v[28:29] op_sel_hi:[1,0]
	v_pk_mul_f32 v[30:31], v[36:37], v[28:29] op_sel_hi:[1,0]
	v_pk_mul_f32 v[26:27], v[26:27], v[28:29] op_sel_hi:[1,0]
	v_pk_mul_f32 v[28:29], v[32:33], v[28:29] op_sel_hi:[1,0]
	v_pk_mul_f32 v[24:25], v[0:1], v[24:25]
	v_pk_mul_f32 v[30:31], v[2:3], v[30:31]
	v_pk_mul_f32 v[26:27], v[4:5], v[26:27]
	v_pk_mul_f32 v[28:29], v[6:7], v[28:29]
	v_cvt_pk_bf16_f32 v24, v24, v25
	v_cvt_pk_bf16_f32 v25, v30, v31
	v_cvt_pk_bf16_f32 v26, v26, v27
	v_cvt_pk_bf16_f32 v27, v28, v29
	v_lshl_add_u64 v[28:29], s[36:37], 0, v[52:53]
	global_store_dwordx4 v[28:29], v[24:27], off
	s_waitcnt vmcnt(4)
	v_lshlrev_b32_e32 v28, 16, v18
	v_and_b32_e32 v29, 0xffff0000, v18
	v_lshlrev_b32_e32 v24, 16, v19
	v_and_b32_e32 v25, 0xffff0000, v19
	s_waitcnt vmcnt(3)
	v_lshlrev_b32_e32 v18, 16, v22
	v_and_b32_e32 v19, 0xffff0000, v22
	v_pk_fma_f32 v[18:19], v[12:13], v[18:19], v[28:29]
	v_lshlrev_b32_e32 v28, 16, v17
	v_and_b32_e32 v29, 0xffff0000, v17
	v_lshlrev_b32_e32 v32, 16, v16
	v_and_b32_e32 v33, 0xffff0000, v16
	v_lshlrev_b32_e32 v16, 16, v20
	v_and_b32_e32 v17, 0xffff0000, v20
	v_lshlrev_b32_e32 v30, 16, v21
	v_and_b32_e32 v31, 0xffff0000, v21
	v_pk_fma_f32 v[16:17], v[8:9], v[16:17], v[32:33]
	v_pk_fma_f32 v[28:29], v[10:11], v[30:31], v[28:29]
	v_pk_mul_f32 v[20:21], v[16:17], v[16:17]
	v_pk_mul_f32 v[30:31], v[28:29], v[28:29]
	v_add_f32_e32 v20, v20, v21
	v_add_f32_e32 v20, v30, v20
	v_lshlrev_b32_e32 v26, 16, v23
	v_and_b32_e32 v27, 0xffff0000, v23
	v_pk_mul_f32 v[22:23], v[18:19], v[18:19]
	v_add_f32_e32 v20, v31, v20
	v_pk_fma_f32 v[24:25], v[14:15], v[26:27], v[24:25]
	v_add_f32_e32 v20, v22, v20
	v_pk_mul_f32 v[26:27], v[24:25], v[24:25]
	v_add_f32_e32 v20, v23, v20
	v_add_f32_e32 v20, v26, v20
	v_add_f32_e32 v20, v27, v20
	s_waitcnt lgkmcnt(0)
	s_waitcnt lgkmcnt(0)
	s_waitcnt lgkmcnt(0)
	s_waitcnt lgkmcnt(0)
	s_waitcnt lgkmcnt(0)
	s_waitcnt lgkmcnt(0)
	s_nop 1
	v_add_f32_dpp v20, v20, v20 quad_perm:[1,0,3,2] row_mask:0xf bank_mask:0xf
	s_nop 1
	v_add_f32_dpp v20, v20, v20 quad_perm:[2,3,0,1] row_mask:0xf bank_mask:0xf
	s_nop 1
	v_add_f32_dpp v20, v20, v20 row_half_mirror row_mask:0xf bank_mask:0xf
	s_nop 1
	v_add_f32_dpp v20, v20, v20 row_mirror row_mask:0xf bank_mask:0xf
	s_nop 1
	v_readlane_b32 s98, v20, 0
	v_readlane_b32 s99, v20, 16
	v_readlane_b32 s100, v20, 32
	v_readlane_b32 s101, v20, 48
	s_nop 1
	v_mov_b32_e32 v20, s98
	v_add_f32_e32 v20, s99, v20
	v_add_f32_e32 v20, s100, v20
	v_add_f32_e32 v20, s101, v20
	v_fmamk_f32 v20, v20, 0x3b000000, v77
	v_rsq_f32_e32 v20, v20
	s_nop 0
	v_pk_mul_f32 v[16:17], v[16:17], v[20:21] op_sel_hi:[1,0]
	v_pk_mul_f32 v[22:23], v[28:29], v[20:21] op_sel_hi:[1,0]
	v_pk_mul_f32 v[18:19], v[18:19], v[20:21] op_sel_hi:[1,0]
	v_pk_mul_f32 v[20:21], v[24:25], v[20:21] op_sel_hi:[1,0]
	v_pk_mul_f32 v[18:19], v[4:5], v[18:19]
	v_pk_mul_f32 v[20:21], v[6:7], v[20:21]
	v_cvt_pk_bf16_f32 v18, v18, v19
	v_cvt_pk_bf16_f32 v19, v20, v21
	v_lshl_add_u64 v[20:21], s[16:17], 0, v[52:53]
	s_add_u32 s16, s16, 0x10000
	s_addc_u32 s17, s17, 0
	s_add_u32 s18, s18, 0x8000
	s_addc_u32 s19, s19, 0
	s_add_u32 s36, s36, 0x10000
	s_addc_u32 s37, s37, 0
	s_add_u32 s38, s38, 0x8000
	s_addc_u32 s39, s39, 0
	s_add_u32 s40, s40, 0x10000
	s_addc_u32 s41, s41, 0
	s_add_u32 s42, s42, 0x8000
	s_addc_u32 s43, s43, 0
	s_add_u32 s60, s60, 0x10000
	s_addc_u32 s61, s61, 0
	s_add_u32 s64, s64, 0x8000
	v_pk_mul_f32 v[16:17], v[0:1], v[16:17]
	v_pk_mul_f32 v[22:23], v[2:3], v[22:23]
	s_addc_u32 s65, s65, 0
	v_cvt_pk_bf16_f32 v16, v16, v17
	v_cvt_pk_bf16_f32 v17, v22, v23
	s_cmpk_lt_u32 s7, 0x60
	global_store_dwordx4 v[20:21], v[16:19], off
	s_cbranch_scc1 .LBB0_574
	s_branch .LBB0_561

.LBB0_1004:
	v_lshl_add_u32 v146, s58, 8, v148
	v_lshl_add_u32 v144, s36, 8, v150
	v_lshlrev_b32_e32 v144, 1, v144
	v_lshl_add_u32 v162, v146, 11, v144
	v_add_u32_e32 v163, 0x8000, v162
	v_add_u32_e32 v164, 0x10000, v162
	v_add_u32_e32 v165, 0x18000, v162
	v_add_u32_e32 v166, 0x40000, v162
	v_add_u32_e32 v167, 0x48000, v162
	v_add_u32_e32 v168, 0x50000, v162
	v_add_u32_e32 v169, 0x58000, v162
	global_load_dwordx4 v[186:189], v162, s[34:35]
	global_load_dwordx4 v[190:193], v162, s[34:35] offset:256
	global_load_dwordx4 v[194:197], v163, s[34:35]
	global_load_dwordx4 v[198:201], v163, s[34:35] offset:256
	global_load_dwordx4 v[202:205], v164, s[34:35]
	global_load_dwordx4 v[206:209], v164, s[34:35] offset:256
	global_load_dwordx4 v[210:213], v165, s[34:35]
	global_load_dwordx4 v[214:217], v165, s[34:35] offset:256
	global_load_dwordx4 v[224:227], v166, s[34:35]
	global_load_dwordx4 v[228:231], v166, s[34:35] offset:256
	global_load_dwordx4 v[232:235], v167, s[34:35]
	global_load_dwordx4 v[236:239], v167, s[34:35] offset:256
	global_load_dwordx4 v[240:243], v168, s[34:35]
	global_load_dwordx4 v[244:247], v168, s[34:35] offset:256
	global_load_dwordx4 v[154:157], v169, s[34:35]
	global_load_dwordx4 v[158:161], v169, s[34:35] offset:256
	s_and_b64 vcc, exec, s[94:95]
	s_cbranch_vccz .LBB0_1006
	s_barrier
.LBB0_1006:
	s_lshl_b32 s44, s36, 2
	s_add_u32 s44, s44, s29
	s_lshl_b32 s44, s44, 2
	v_lshl_add_u32 v170, v146, 6, s44
	v_add_u32_e32 v171, 0x2000, v170
	s_waitcnt vmcnt(14)
	v_lshlrev_b32_e32 v172, 16, v186
	v_and_b32_e32 v173, 0xffff0000, v186
	v_lshlrev_b32_e32 v186, 16, v187
	v_and_b32_e32 v187, 0xffff0000, v187
	v_lshlrev_b32_e32 v174, 16, v188
	v_and_b32_e32 v175, 0xffff0000, v188
	v_lshlrev_b32_e32 v188, 16, v189
	v_and_b32_e32 v189, 0xffff0000, v189
	v_pk_add_f32 v[126:127], v[126:127], v[186:187]
	v_pk_add_f32 v[124:125], v[124:125], v[172:173]
	v_pk_add_f32 v[122:123], v[122:123], v[188:189]
	v_pk_add_f32 v[120:121], v[120:121], v[174:175]
	v_lshlrev_b32_e32 v176, 16, v190
	v_and_b32_e32 v177, 0xffff0000, v190
	v_lshlrev_b32_e32 v190, 16, v191
	v_and_b32_e32 v191, 0xffff0000, v191
	v_lshlrev_b32_e32 v178, 16, v192
	v_and_b32_e32 v179, 0xffff0000, v192
	v_lshlrev_b32_e32 v192, 16, v193
	v_and_b32_e32 v193, 0xffff0000, v193
	v_pk_add_f32 v[118:119], v[118:119], v[190:191]
	v_pk_add_f32 v[116:117], v[116:117], v[176:177]
	v_pk_add_f32 v[114:115], v[114:115], v[192:193]
	v_pk_add_f32 v[112:113], v[112:113], v[178:179]
	v_mul_f32_e32 v180, v125, v125
	v_mul_f32_e32 v181, v127, v127
	v_mul_f32_e32 v182, v121, v121
	v_mul_f32_e32 v183, v123, v123
	v_fmac_f32_e32 v180, v124, v124
	v_fmac_f32_e32 v181, v126, v126
	v_fmac_f32_e32 v182, v120, v120
	v_fmac_f32_e32 v183, v122, v122
	v_add_f32_e32 v180, v180, v181
	v_add_f32_e32 v182, v182, v183
	v_add_f32_e32 v180, v180, v182
	v_mul_f32_e32 v147, v117, v117
	v_mul_f32_e32 v181, v119, v119
	v_mul_f32_e32 v182, v113, v113
	v_mul_f32_e32 v183, v115, v115
	v_fmac_f32_e32 v147, v116, v116
	v_fmac_f32_e32 v181, v118, v118
	v_fmac_f32_e32 v182, v112, v112
	v_fmac_f32_e32 v183, v114, v114
	v_add_f32_e32 v147, v147, v181
	v_add_f32_e32 v182, v182, v183
	v_add_f32_e32 v147, v147, v182
	v_add_f32_e32 v147, v180, v147
	ds_bpermute_b32 v145, v222, v147
	v_cvt_pk_bf16_f32 v124, v124, v125
	v_cvt_pk_bf16_f32 v125, v126, v127
	v_cvt_pk_bf16_f32 v126, v120, v121
	v_cvt_pk_bf16_f32 v127, v122, v123
	global_store_dwordx4 v162, v[124:127], s[34:35]
	s_waitcnt lgkmcnt(0)
	v_add_f32_e32 v147, v147, v145
	ds_bpermute_b32 v145, v223, v147
	v_cvt_pk_bf16_f32 v116, v116, v117
	v_cvt_pk_bf16_f32 v117, v118, v119
	v_cvt_pk_bf16_f32 v118, v112, v113
	v_cvt_pk_bf16_f32 v119, v114, v115
	global_store_dwordx4 v162, v[116:119], s[34:35] offset:256
	s_waitcnt lgkmcnt(0)
	v_add_f32_e32 v147, v147, v145
	s_and_saveexec_b64 s[46:47], s[10:11]
	global_store_dword v170, v147, s[38:39] offset:0
	s_mov_b64 exec, s[46:47]
	s_waitcnt vmcnt(15)
	v_lshlrev_b32_e32 v172, 16, v194
	v_and_b32_e32 v173, 0xffff0000, v194
	v_lshlrev_b32_e32 v194, 16, v195
	v_and_b32_e32 v195, 0xffff0000, v195
	v_lshlrev_b32_e32 v174, 16, v196
	v_and_b32_e32 v175, 0xffff0000, v196
	v_lshlrev_b32_e32 v196, 16, v197
	v_and_b32_e32 v197, 0xffff0000, v197
	v_pk_add_f32 v[110:111], v[110:111], v[194:195]
	v_pk_add_f32 v[108:109], v[108:109], v[172:173]
	v_pk_add_f32 v[106:107], v[106:107], v[196:197]
	v_pk_add_f32 v[104:105], v[104:105], v[174:175]
	v_lshlrev_b32_e32 v176, 16, v198
	v_and_b32_e32 v177, 0xffff0000, v198
	v_lshlrev_b32_e32 v198, 16, v199
	v_and_b32_e32 v199, 0xffff0000, v199
	v_lshlrev_b32_e32 v178, 16, v200
	v_and_b32_e32 v179, 0xffff0000, v200
	v_lshlrev_b32_e32 v200, 16, v201
	v_and_b32_e32 v201, 0xffff0000, v201
	v_pk_add_f32 v[102:103], v[102:103], v[198:199]
	v_pk_add_f32 v[100:101], v[100:101], v[176:177]
	v_pk_add_f32 v[98:99], v[98:99], v[200:201]
	v_pk_add_f32 v[96:97], v[96:97], v[178:179]
	v_mul_f32_e32 v180, v109, v109
	v_mul_f32_e32 v181, v111, v111
	v_mul_f32_e32 v182, v105, v105
	v_mul_f32_e32 v183, v107, v107
	v_fmac_f32_e32 v180, v108, v108
	v_fmac_f32_e32 v181, v110, v110
	v_fmac_f32_e32 v182, v104, v104
	v_fmac_f32_e32 v183, v106, v106
	v_add_f32_e32 v180, v180, v181
	v_add_f32_e32 v182, v182, v183
	v_add_f32_e32 v180, v180, v182
	v_mul_f32_e32 v147, v101, v101
	v_mul_f32_e32 v181, v103, v103
	v_mul_f32_e32 v182, v97, v97
	v_mul_f32_e32 v183, v99, v99
	v_fmac_f32_e32 v147, v100, v100
	v_fmac_f32_e32 v181, v102, v102
	v_fmac_f32_e32 v182, v96, v96
	v_fmac_f32_e32 v183, v98, v98
	v_add_f32_e32 v147, v147, v181
	v_add_f32_e32 v182, v182, v183
	v_add_f32_e32 v147, v147, v182
	v_add_f32_e32 v147, v180, v147
	ds_bpermute_b32 v145, v222, v147
	v_cvt_pk_bf16_f32 v108, v108, v109
	v_cvt_pk_bf16_f32 v109, v110, v111
	v_cvt_pk_bf16_f32 v110, v104, v105
	v_cvt_pk_bf16_f32 v111, v106, v107
	global_store_dwordx4 v163, v[108:111], s[34:35]
	s_waitcnt lgkmcnt(0)
	v_add_f32_e32 v147, v147, v145
	ds_bpermute_b32 v145, v223, v147
	v_cvt_pk_bf16_f32 v100, v100, v101
	v_cvt_pk_bf16_f32 v101, v102, v103
	v_cvt_pk_bf16_f32 v102, v96, v97
	v_cvt_pk_bf16_f32 v103, v98, v99
	global_store_dwordx4 v163, v[100:103], s[34:35] offset:256
	s_waitcnt lgkmcnt(0)
	v_add_f32_e32 v147, v147, v145
	s_and_saveexec_b64 s[46:47], s[10:11]
	global_store_dword v170, v147, s[38:39] offset:1024
	s_mov_b64 exec, s[46:47]
	s_waitcnt vmcnt(16)
	v_lshlrev_b32_e32 v172, 16, v202
	v_and_b32_e32 v173, 0xffff0000, v202
	v_lshlrev_b32_e32 v202, 16, v203
	v_and_b32_e32 v203, 0xffff0000, v203
	v_lshlrev_b32_e32 v174, 16, v204
	v_and_b32_e32 v175, 0xffff0000, v204
	v_lshlrev_b32_e32 v204, 16, v205
	v_and_b32_e32 v205, 0xffff0000, v205
	v_pk_add_f32 v[94:95], v[94:95], v[202:203]
	v_pk_add_f32 v[92:93], v[92:93], v[172:173]
	v_pk_add_f32 v[90:91], v[90:91], v[204:205]
	v_pk_add_f32 v[88:89], v[88:89], v[174:175]
	v_lshlrev_b32_e32 v176, 16, v206
	v_and_b32_e32 v177, 0xffff0000, v206
	v_lshlrev_b32_e32 v206, 16, v207
	v_and_b32_e32 v207, 0xffff0000, v207
	v_lshlrev_b32_e32 v178, 16, v208
	v_and_b32_e32 v179, 0xffff0000, v208
	v_lshlrev_b32_e32 v208, 16, v209
	v_and_b32_e32 v209, 0xffff0000, v209
	v_pk_add_f32 v[86:87], v[86:87], v[206:207]
	v_pk_add_f32 v[84:85], v[84:85], v[176:177]
	v_pk_add_f32 v[82:83], v[82:83], v[208:209]
	v_pk_add_f32 v[80:81], v[80:81], v[178:179]
	v_mul_f32_e32 v180, v93, v93
	v_mul_f32_e32 v181, v95, v95
	v_mul_f32_e32 v182, v89, v89
	v_mul_f32_e32 v183, v91, v91
	v_fmac_f32_e32 v180, v92, v92
	v_fmac_f32_e32 v181, v94, v94
	v_fmac_f32_e32 v182, v88, v88
	v_fmac_f32_e32 v183, v90, v90
	v_add_f32_e32 v180, v180, v181
	v_add_f32_e32 v182, v182, v183
	v_add_f32_e32 v180, v180, v182
	v_mul_f32_e32 v147, v85, v85
	v_mul_f32_e32 v181, v87, v87
	v_mul_f32_e32 v182, v81, v81
	v_mul_f32_e32 v183, v83, v83
	v_fmac_f32_e32 v147, v84, v84
	v_fmac_f32_e32 v181, v86, v86
	v_fmac_f32_e32 v182, v80, v80
	v_fmac_f32_e32 v183, v82, v82
	v_add_f32_e32 v147, v147, v181
	v_add_f32_e32 v182, v182, v183
	v_add_f32_e32 v147, v147, v182
	v_add_f32_e32 v147, v180, v147
	ds_bpermute_b32 v145, v222, v147
	v_cvt_pk_bf16_f32 v92, v92, v93
	v_cvt_pk_bf16_f32 v93, v94, v95
	v_cvt_pk_bf16_f32 v94, v88, v89
	v_cvt_pk_bf16_f32 v95, v90, v91
	global_store_dwordx4 v164, v[92:95], s[34:35]
	s_waitcnt lgkmcnt(0)
	v_add_f32_e32 v147, v147, v145
	ds_bpermute_b32 v145, v223, v147
	v_cvt_pk_bf16_f32 v84, v84, v85
	v_cvt_pk_bf16_f32 v85, v86, v87
	v_cvt_pk_bf16_f32 v86, v80, v81
	v_cvt_pk_bf16_f32 v87, v82, v83
	global_store_dwordx4 v164, v[84:87], s[34:35] offset:256
	s_waitcnt lgkmcnt(0)
	v_add_f32_e32 v147, v147, v145
	s_and_saveexec_b64 s[46:47], s[10:11]
	global_store_dword v170, v147, s[38:39] offset:2048
	s_mov_b64 exec, s[46:47]
	s_waitcnt vmcnt(17)
	v_lshlrev_b32_e32 v172, 16, v210
	v_and_b32_e32 v173, 0xffff0000, v210
	v_lshlrev_b32_e32 v210, 16, v211
	v_and_b32_e32 v211, 0xffff0000, v211
	v_lshlrev_b32_e32 v174, 16, v212
	v_and_b32_e32 v175, 0xffff0000, v212
	v_lshlrev_b32_e32 v212, 16, v213
	v_and_b32_e32 v213, 0xffff0000, v213
	v_pk_add_f32 v[78:79], v[78:79], v[210:211]
	v_pk_add_f32 v[76:77], v[76:77], v[172:173]
	v_pk_add_f32 v[74:75], v[74:75], v[212:213]
	v_pk_add_f32 v[72:73], v[72:73], v[174:175]
	v_lshlrev_b32_e32 v176, 16, v214
	v_and_b32_e32 v177, 0xffff0000, v214
	v_lshlrev_b32_e32 v214, 16, v215
	v_and_b32_e32 v215, 0xffff0000, v215
	v_lshlrev_b32_e32 v178, 16, v216
	v_and_b32_e32 v179, 0xffff0000, v216
	v_lshlrev_b32_e32 v216, 16, v217
	v_and_b32_e32 v217, 0xffff0000, v217
	v_pk_add_f32 v[70:71], v[70:71], v[214:215]
	v_pk_add_f32 v[68:69], v[68:69], v[176:177]
	v_pk_add_f32 v[66:67], v[66:67], v[216:217]
	v_pk_add_f32 v[64:65], v[64:65], v[178:179]
	v_mul_f32_e32 v180, v77, v77
	v_mul_f32_e32 v181, v79, v79
	v_mul_f32_e32 v182, v73, v73
	v_mul_f32_e32 v183, v75, v75
	v_fmac_f32_e32 v180, v76, v76
	v_fmac_f32_e32 v181, v78, v78
	v_fmac_f32_e32 v182, v72, v72
	v_fmac_f32_e32 v183, v74, v74
	v_add_f32_e32 v180, v180, v181
	v_add_f32_e32 v182, v182, v183
	v_add_f32_e32 v180, v180, v182
	v_mul_f32_e32 v147, v69, v69
	v_mul_f32_e32 v181, v71, v71
	v_mul_f32_e32 v182, v65, v65
	v_mul_f32_e32 v183, v67, v67
	v_fmac_f32_e32 v147, v68, v68
	v_fmac_f32_e32 v181, v70, v70
	v_fmac_f32_e32 v182, v64, v64
	v_fmac_f32_e32 v183, v66, v66
	v_add_f32_e32 v147, v147, v181
	v_add_f32_e32 v182, v182, v183
	v_add_f32_e32 v147, v147, v182
	v_add_f32_e32 v147, v180, v147
	ds_bpermute_b32 v145, v222, v147
	v_cvt_pk_bf16_f32 v76, v76, v77
	v_cvt_pk_bf16_f32 v77, v78, v79
	v_cvt_pk_bf16_f32 v78, v72, v73
	v_cvt_pk_bf16_f32 v79, v74, v75
	global_store_dwordx4 v165, v[76:79], s[34:35]
	s_waitcnt lgkmcnt(0)
	v_add_f32_e32 v147, v147, v145
	ds_bpermute_b32 v145, v223, v147
	v_cvt_pk_bf16_f32 v68, v68, v69
	v_cvt_pk_bf16_f32 v69, v70, v71
	v_cvt_pk_bf16_f32 v70, v64, v65
	v_cvt_pk_bf16_f32 v71, v66, v67
	global_store_dwordx4 v165, v[68:71], s[34:35] offset:256
	s_waitcnt lgkmcnt(0)
	v_add_f32_e32 v147, v147, v145
	s_and_saveexec_b64 s[46:47], s[10:11]
	global_store_dword v170, v147, s[38:39] offset:3072
	s_mov_b64 exec, s[46:47]
	s_waitcnt vmcnt(18)
	v_lshlrev_b32_e32 v172, 16, v224
	v_and_b32_e32 v173, 0xffff0000, v224
	v_lshlrev_b32_e32 v224, 16, v225
	v_and_b32_e32 v225, 0xffff0000, v225
	v_lshlrev_b32_e32 v174, 16, v226
	v_and_b32_e32 v175, 0xffff0000, v226
	v_lshlrev_b32_e32 v226, 16, v227
	v_and_b32_e32 v227, 0xffff0000, v227
	v_pk_add_f32 v[62:63], v[62:63], v[224:225]
	v_pk_add_f32 v[60:61], v[60:61], v[172:173]
	v_pk_add_f32 v[58:59], v[58:59], v[226:227]
	v_pk_add_f32 v[56:57], v[56:57], v[174:175]
	v_lshlrev_b32_e32 v176, 16, v228
	v_and_b32_e32 v177, 0xffff0000, v228
	v_lshlrev_b32_e32 v228, 16, v229
	v_and_b32_e32 v229, 0xffff0000, v229
	v_lshlrev_b32_e32 v178, 16, v230
	v_and_b32_e32 v179, 0xffff0000, v230
	v_lshlrev_b32_e32 v230, 16, v231
	v_and_b32_e32 v231, 0xffff0000, v231
	v_pk_add_f32 v[54:55], v[54:55], v[228:229]
	v_pk_add_f32 v[52:53], v[52:53], v[176:177]
	v_pk_add_f32 v[50:51], v[50:51], v[230:231]
	v_pk_add_f32 v[48:49], v[48:49], v[178:179]
	v_mul_f32_e32 v180, v61, v61
	v_mul_f32_e32 v181, v63, v63
	v_mul_f32_e32 v182, v57, v57
	v_mul_f32_e32 v183, v59, v59
	v_fmac_f32_e32 v180, v60, v60
	v_fmac_f32_e32 v181, v62, v62
	v_fmac_f32_e32 v182, v56, v56
	v_fmac_f32_e32 v183, v58, v58
	v_add_f32_e32 v180, v180, v181
	v_add_f32_e32 v182, v182, v183
	v_add_f32_e32 v180, v180, v182
	v_mul_f32_e32 v147, v53, v53
	v_mul_f32_e32 v181, v55, v55
	v_mul_f32_e32 v182, v49, v49
	v_mul_f32_e32 v183, v51, v51
	v_fmac_f32_e32 v147, v52, v52
	v_fmac_f32_e32 v181, v54, v54
	v_fmac_f32_e32 v182, v48, v48
	v_fmac_f32_e32 v183, v50, v50
	v_add_f32_e32 v147, v147, v181
	v_add_f32_e32 v182, v182, v183
	v_add_f32_e32 v147, v147, v182
	v_add_f32_e32 v147, v180, v147
	ds_bpermute_b32 v145, v222, v147
	v_cvt_pk_bf16_f32 v60, v60, v61
	v_cvt_pk_bf16_f32 v61, v62, v63
	v_cvt_pk_bf16_f32 v62, v56, v57
	v_cvt_pk_bf16_f32 v63, v58, v59
	global_store_dwordx4 v166, v[60:63], s[34:35]
	s_waitcnt lgkmcnt(0)
	v_add_f32_e32 v147, v147, v145
	ds_bpermute_b32 v145, v223, v147
	v_cvt_pk_bf16_f32 v52, v52, v53
	v_cvt_pk_bf16_f32 v53, v54, v55
	v_cvt_pk_bf16_f32 v54, v48, v49
	v_cvt_pk_bf16_f32 v55, v50, v51
	global_store_dwordx4 v166, v[52:55], s[34:35] offset:256
	s_waitcnt lgkmcnt(0)
	v_add_f32_e32 v147, v147, v145
	s_and_saveexec_b64 s[46:47], s[10:11]
	global_store_dword v171, v147, s[38:39] offset:0
	s_mov_b64 exec, s[46:47]
	s_waitcnt vmcnt(19)
	v_lshlrev_b32_e32 v172, 16, v232
	v_and_b32_e32 v173, 0xffff0000, v232
	v_lshlrev_b32_e32 v232, 16, v233
	v_and_b32_e32 v233, 0xffff0000, v233
	v_lshlrev_b32_e32 v174, 16, v234
	v_and_b32_e32 v175, 0xffff0000, v234
	v_lshlrev_b32_e32 v234, 16, v235
	v_and_b32_e32 v235, 0xffff0000, v235
	v_pk_add_f32 v[46:47], v[46:47], v[232:233]
	v_pk_add_f32 v[44:45], v[44:45], v[172:173]
	v_pk_add_f32 v[42:43], v[42:43], v[234:235]
	v_pk_add_f32 v[40:41], v[40:41], v[174:175]
	v_lshlrev_b32_e32 v176, 16, v236
	v_and_b32_e32 v177, 0xffff0000, v236
	v_lshlrev_b32_e32 v236, 16, v237
	v_and_b32_e32 v237, 0xffff0000, v237
	v_lshlrev_b32_e32 v178, 16, v238
	v_and_b32_e32 v179, 0xffff0000, v238
	v_lshlrev_b32_e32 v238, 16, v239
	v_and_b32_e32 v239, 0xffff0000, v239
	v_pk_add_f32 v[38:39], v[38:39], v[236:237]
	v_pk_add_f32 v[36:37], v[36:37], v[176:177]
	v_pk_add_f32 v[34:35], v[34:35], v[238:239]
	v_pk_add_f32 v[32:33], v[32:33], v[178:179]
	v_mul_f32_e32 v180, v45, v45
	v_mul_f32_e32 v181, v47, v47
	v_mul_f32_e32 v182, v41, v41
	v_mul_f32_e32 v183, v43, v43
	v_fmac_f32_e32 v180, v44, v44
	v_fmac_f32_e32 v181, v46, v46
	v_fmac_f32_e32 v182, v40, v40
	v_fmac_f32_e32 v183, v42, v42
	v_add_f32_e32 v180, v180, v181
	v_add_f32_e32 v182, v182, v183
	v_add_f32_e32 v180, v180, v182
	v_mul_f32_e32 v147, v37, v37
	v_mul_f32_e32 v181, v39, v39
	v_mul_f32_e32 v182, v33, v33
	v_mul_f32_e32 v183, v35, v35
	v_fmac_f32_e32 v147, v36, v36
	v_fmac_f32_e32 v181, v38, v38
	v_fmac_f32_e32 v182, v32, v32
	v_fmac_f32_e32 v183, v34, v34
	v_add_f32_e32 v147, v147, v181
	v_add_f32_e32 v182, v182, v183
	v_add_f32_e32 v147, v147, v182
	v_add_f32_e32 v147, v180, v147
	ds_bpermute_b32 v145, v222, v147
	v_cvt_pk_bf16_f32 v44, v44, v45
	v_cvt_pk_bf16_f32 v45, v46, v47
	v_cvt_pk_bf16_f32 v46, v40, v41
	v_cvt_pk_bf16_f32 v47, v42, v43
	global_store_dwordx4 v167, v[44:47], s[34:35]
	s_waitcnt lgkmcnt(0)
	v_add_f32_e32 v147, v147, v145
	ds_bpermute_b32 v145, v223, v147
	v_cvt_pk_bf16_f32 v36, v36, v37
	v_cvt_pk_bf16_f32 v37, v38, v39
	v_cvt_pk_bf16_f32 v38, v32, v33
	v_cvt_pk_bf16_f32 v39, v34, v35
	global_store_dwordx4 v167, v[36:39], s[34:35] offset:256
	s_waitcnt lgkmcnt(0)
	v_add_f32_e32 v147, v147, v145
	s_and_saveexec_b64 s[46:47], s[10:11]
	global_store_dword v171, v147, s[38:39] offset:1024
	s_mov_b64 exec, s[46:47]
	s_waitcnt vmcnt(20)
	v_lshlrev_b32_e32 v172, 16, v240
	v_and_b32_e32 v173, 0xffff0000, v240
	v_lshlrev_b32_e32 v240, 16, v241
	v_and_b32_e32 v241, 0xffff0000, v241
	v_lshlrev_b32_e32 v174, 16, v242
	v_and_b32_e32 v175, 0xffff0000, v242
	v_lshlrev_b32_e32 v242, 16, v243
	v_and_b32_e32 v243, 0xffff0000, v243
	v_pk_add_f32 v[30:31], v[30:31], v[240:241]
	v_pk_add_f32 v[28:29], v[28:29], v[172:173]
	v_pk_add_f32 v[26:27], v[26:27], v[242:243]
	v_pk_add_f32 v[24:25], v[24:25], v[174:175]
	v_lshlrev_b32_e32 v176, 16, v244
	v_and_b32_e32 v177, 0xffff0000, v244
	v_lshlrev_b32_e32 v244, 16, v245
	v_and_b32_e32 v245, 0xffff0000, v245
	v_lshlrev_b32_e32 v178, 16, v246
	v_and_b32_e32 v179, 0xffff0000, v246
	v_lshlrev_b32_e32 v246, 16, v247
	v_and_b32_e32 v247, 0xffff0000, v247
	v_pk_add_f32 v[22:23], v[22:23], v[244:245]
	v_pk_add_f32 v[20:21], v[20:21], v[176:177]
	v_pk_add_f32 v[18:19], v[18:19], v[246:247]
	v_pk_add_f32 v[16:17], v[16:17], v[178:179]
	v_mul_f32_e32 v180, v29, v29
	v_mul_f32_e32 v181, v31, v31
	v_mul_f32_e32 v182, v25, v25
	v_mul_f32_e32 v183, v27, v27
	v_fmac_f32_e32 v180, v28, v28
	v_fmac_f32_e32 v181, v30, v30
	v_fmac_f32_e32 v182, v24, v24
	v_fmac_f32_e32 v183, v26, v26
	v_add_f32_e32 v180, v180, v181
	v_add_f32_e32 v182, v182, v183
	v_add_f32_e32 v180, v180, v182
	v_mul_f32_e32 v147, v21, v21
	v_mul_f32_e32 v181, v23, v23
	v_mul_f32_e32 v182, v17, v17
	v_mul_f32_e32 v183, v19, v19
	v_fmac_f32_e32 v147, v20, v20
	v_fmac_f32_e32 v181, v22, v22
	v_fmac_f32_e32 v182, v16, v16
	v_fmac_f32_e32 v183, v18, v18
	v_add_f32_e32 v147, v147, v181
	v_add_f32_e32 v182, v182, v183
	v_add_f32_e32 v147, v147, v182
	v_add_f32_e32 v147, v180, v147
	ds_bpermute_b32 v145, v222, v147
	v_cvt_pk_bf16_f32 v28, v28, v29
	v_cvt_pk_bf16_f32 v29, v30, v31
	v_cvt_pk_bf16_f32 v30, v24, v25
	v_cvt_pk_bf16_f32 v31, v26, v27
	global_store_dwordx4 v168, v[28:31], s[34:35]
	s_waitcnt lgkmcnt(0)
	v_add_f32_e32 v147, v147, v145
	ds_bpermute_b32 v145, v223, v147
	v_cvt_pk_bf16_f32 v20, v20, v21
	v_cvt_pk_bf16_f32 v21, v22, v23
	v_cvt_pk_bf16_f32 v22, v16, v17
	v_cvt_pk_bf16_f32 v23, v18, v19
	global_store_dwordx4 v168, v[20:23], s[34:35] offset:256
	s_waitcnt lgkmcnt(0)
	v_add_f32_e32 v147, v147, v145
	s_and_saveexec_b64 s[46:47], s[10:11]
	global_store_dword v171, v147, s[38:39] offset:2048
	s_mov_b64 exec, s[46:47]
	s_waitcnt vmcnt(21)
	v_lshlrev_b32_e32 v172, 16, v154
	v_and_b32_e32 v173, 0xffff0000, v154
	v_lshlrev_b32_e32 v154, 16, v155
	v_and_b32_e32 v155, 0xffff0000, v155
	v_lshlrev_b32_e32 v174, 16, v156
	v_and_b32_e32 v175, 0xffff0000, v156
	v_lshlrev_b32_e32 v156, 16, v157
	v_and_b32_e32 v157, 0xffff0000, v157
	v_pk_add_f32 v[14:15], v[14:15], v[154:155]
	v_pk_add_f32 v[12:13], v[12:13], v[172:173]
	v_pk_add_f32 v[10:11], v[10:11], v[156:157]
	v_pk_add_f32 v[8:9], v[8:9], v[174:175]
	v_lshlrev_b32_e32 v176, 16, v158
	v_and_b32_e32 v177, 0xffff0000, v158
	v_lshlrev_b32_e32 v158, 16, v159
	v_and_b32_e32 v159, 0xffff0000, v159
	v_lshlrev_b32_e32 v178, 16, v160
	v_and_b32_e32 v179, 0xffff0000, v160
	v_lshlrev_b32_e32 v160, 16, v161
	v_and_b32_e32 v161, 0xffff0000, v161
	v_pk_add_f32 v[6:7], v[6:7], v[158:159]
	v_pk_add_f32 v[4:5], v[4:5], v[176:177]
	v_pk_add_f32 v[2:3], v[2:3], v[160:161]
	v_pk_add_f32 v[0:1], v[0:1], v[178:179]
	v_mul_f32_e32 v180, v13, v13
	v_mul_f32_e32 v181, v15, v15
	v_mul_f32_e32 v182, v9, v9
	v_mul_f32_e32 v183, v11, v11
	v_fmac_f32_e32 v180, v12, v12
	v_fmac_f32_e32 v181, v14, v14
	v_fmac_f32_e32 v182, v8, v8
	v_fmac_f32_e32 v183, v10, v10
	v_add_f32_e32 v180, v180, v181
	v_add_f32_e32 v182, v182, v183
	v_add_f32_e32 v180, v180, v182
	v_mul_f32_e32 v147, v5, v5
	v_mul_f32_e32 v181, v7, v7
	v_mul_f32_e32 v182, v1, v1
	v_mul_f32_e32 v183, v3, v3
	v_fmac_f32_e32 v147, v4, v4
	v_fmac_f32_e32 v181, v6, v6
	v_fmac_f32_e32 v182, v0, v0
	v_fmac_f32_e32 v183, v2, v2
	v_add_f32_e32 v147, v147, v181
	v_add_f32_e32 v182, v182, v183
	v_add_f32_e32 v147, v147, v182
	v_add_f32_e32 v147, v180, v147
	ds_bpermute_b32 v145, v222, v147
	v_cvt_pk_bf16_f32 v12, v12, v13
	v_cvt_pk_bf16_f32 v13, v14, v15
	v_cvt_pk_bf16_f32 v14, v8, v9
	v_cvt_pk_bf16_f32 v15, v10, v11
	global_store_dwordx4 v169, v[12:15], s[34:35]
	s_waitcnt lgkmcnt(0)
	v_add_f32_e32 v147, v147, v145
	ds_bpermute_b32 v145, v223, v147
	v_cvt_pk_bf16_f32 v4, v4, v5
	v_cvt_pk_bf16_f32 v5, v6, v7
	v_cvt_pk_bf16_f32 v6, v0, v1
	v_cvt_pk_bf16_f32 v7, v2, v3
	global_store_dwordx4 v169, v[4:7], s[34:35] offset:256
	s_waitcnt lgkmcnt(0)
	v_add_f32_e32 v147, v147, v145
	s_and_saveexec_b64 s[46:47], s[10:11]
	global_store_dword v171, v147, s[38:39] offset:3072

	.amdhsa_kernel _Z14fwd_megakernel6Params
		.amdhsa_group_segment_fixed_size 0
		.amdhsa_private_segment_fixed_size 0
		.amdhsa_kernarg_size 512
		.amdhsa_user_sgpr_count 2
		.amdhsa_user_sgpr_dispatch_ptr 0
		.amdhsa_user_sgpr_queue_ptr 0
		.amdhsa_user_sgpr_kernarg_segment_ptr 1
		.amdhsa_user_sgpr_dispatch_id 0
		.amdhsa_user_sgpr_kernarg_preload_length 0
		.amdhsa_user_sgpr_kernarg_preload_offset 0
		.amdhsa_user_sgpr_private_segment_size 0
		.amdhsa_uses_dynamic_stack 0
		.amdhsa_enable_private_segment 0
		.amdhsa_system_sgpr_workgroup_id_x 1
		.amdhsa_system_sgpr_workgroup_id_y 0
		.amdhsa_system_sgpr_workgroup_id_z 0
		.amdhsa_system_sgpr_workgroup_info 0
		.amdhsa_system_vgpr_workitem_id 2
		.amdhsa_next_free_vgpr 256
		.amdhsa_next_free_sgpr 102
		.amdhsa_accum_offset 256
		.amdhsa_reserve_vcc 1
		.amdhsa_float_round_mode_32 0
		.amdhsa_float_round_mode_16_64 0
		.amdhsa_float_denorm_mode_32 3
		.amdhsa_float_denorm_mode_16_64 3
		.amdhsa_dx10_clamp 1
		.amdhsa_ieee_mode 1
		.amdhsa_fp16_overflow 0
		.amdhsa_tg_split 0
		.amdhsa_exception_fp_ieee_invalid_op 0
		.amdhsa_exception_fp_denorm_src 0
		.amdhsa_exception_fp_ieee_div_zero 0
		.amdhsa_exception_fp_ieee_overflow 0
		.amdhsa_exception_fp_ieee_underflow 0
		.amdhsa_exception_fp_ieee_inexact 0
		.amdhsa_exception_int_div_zero 0
	.end_amdhsa_kernel
